# waves 0-3 s_setprio 1 in the prompt attention loop; waves 4-7 write the next K/V tile into LDS at the top of the iteration (loads issued one iteration ahead) instead of at the end
# speedup vs baseline: 1.0017x; 1.0009x over previous
; #define LAS __attribute__((address_space(3)))
; #define GAS __attribute__((address_space(1)))
; #define ATT_ISSUE(t) do { const int trow_ = (sample && (t) == 32) ? kvnew : kv0 + 64 * (t); \
;         _Pragma("unroll") for (int i_ = 0; i_ < 3; ++i_) kreg[i_] = *(const GAS u32x4*)(kb[i_] + (size_t)trow_ * ks[i_]); \
;         _Pragma("unroll") for (int i_ = 0; i_ < 2; ++i_) vreg[i_] = *(const GAS u32x4*)(vb[i_] + (size_t)trow_ * 2); } while (0)
; __device__ __forceinline__ void unit(LAS unsigned char* lds, const Tensors& T, int h, int qrow0, int nact, bool sample, int limbase, int kv0, int kvnew, int nt) {
;     ...
;     const int tid = tid_, lane = tid & 63, r32 = lane & 31, hi = lane >> 5; const int wid = __builtin_amdgcn_readfirstlane(tid >> 6);
;     const bool active = wid < nact;
;     const int lim = sample ? limbase : limbase + (wid >> 1);
;     const char* kb[3]; int ks[3]; unsigned kd[3];
; #pragma unroll
;     for (int i = 0; i < 3; ++i) { const int c = tid + 512 * i, row = c / 24, cc = c % 24;
;         if (cc < 16) { kb[i] = (const char*)T.KN + ((size_t)row * DM + h * 128 + cc * 8) * 2; ks[i] = DM * 2; }
;         else { kb[i] = (const char*)T.KPE + ((size_t)row * 64 + (cc - 16) * 8) * 2; ks[i] = 64 * 2; }
;         kd[i] = (unsigned)(row * KP + cc * 16); }
;     const char* vb[2]; unsigned vd[2];
; #pragma unroll
;     for (int i = 0; i < 2; ++i) { const int c = tid + 512 * i, drow = c >> 3, cc = c & 7;
;         vb[i] = (const char*)T.VT + ((size_t)(h * 128 + drow) * TA + cc * 8) * 2; vd[i] = (unsigned)(drow * VP + (cc >> 1) * 32 + (cc & 1) * 8); }
;     u32x4 kreg[3], vreg[2];
;     ...
;     ATT_ISSUE(0);
;     bf16x8 qf[12];
;     { const bf16_t* qrow = T.Q + (size_t)(qrow0 + 32 * (active ? wid : 0) + r32) * NQ + h * QKD + hi * 8;
; #pragma unroll
;       for (int d0 = 0; d0 < 12; ++d0) qf[d0] = *(const GAS bf16x8*)(qrow + d0 * 16); }
;     float mrun = -1e30f, lrun = 0.f;
;     f32x16 o[4];
; #pragma unroll
;     for (int d = 0; d < 4; ++d)
; #pragma unroll
;         for (int r = 0; r < 16; ++r) o[d][r] = 0.f;
;     LAS float* scr = (LAS float*)(lds + OFF_SCR + wid * 256);
.LBB0_891:
	v_mov_b32_e32 v214, v206
	s_mov_b32 s0, 0x2aaaaaab
	s_nop 0
	v_mul_hi_i32 v0, v214, s0
	v_lshrrev_b32_e32 v1, 31, v0
	v_ashrrev_i32_e32 v0, 2, v0
	v_add_u32_e32 v6, v0, v1
	v_mul_lo_u32 v0, v6, 24
	v_sub_u32_e32 v18, v214, v0
	v_readfirstlane_b32 s8, v214
	v_cmp_lt_i32_e32 vcc, 15, v18
	v_ashrrev_i32_e32 v7, 31, v6
	s_and_saveexec_b64 s[0:1], vcc
	s_xor_b64 s[0:1], exec, s[0:1]
	v_lshlrev_b64 v[0:1], 7, v[6:7]
	v_lshl_add_u32 v164, v18, 3, v212
	v_lshl_add_u64 v[0:1], s[34:35], 0, v[0:1]
	v_lshl_add_u64 v[0:1], v[164:165], 1, v[0:1]
	s_or_saveexec_b64 s[0:1], s[0:1]
	v_mov_b64_e32 v[2:3], 0x80
	s_xor_b64 exec, exec, s[0:1]
	v_lshlrev_b64 v[0:1], 10, v[6:7]
	v_lshlrev_b32_e32 v2, 3, v18
	v_or_b32_e32 v0, s2, v0
	v_ashrrev_i32_e32 v3, 31, v2
	v_lshl_add_u64 v[0:1], v[0:1], 0, v[2:3]
	v_lshl_add_u64 v[0:1], v[0:1], 1, s[64:65]
	v_mov_b64_e32 v[2:3], 0x800
	s_or_b64 exec, exec, s[0:1]
	v_add_u32_e32 v7, 0x200, v214
	s_mov_b32 s0, 0x2aaaaaab
	v_mul_hi_i32 v3, v7, s0
	v_lshrrev_b32_e32 v4, 31, v3
	v_ashrrev_i32_e32 v3, 2, v3
	v_add_u32_e32 v12, v3, v4
	v_mul_lo_u32 v3, v12, 24
	v_sub_u32_e32 v3, v7, v3
	v_cmp_lt_i32_e32 vcc, 15, v3
	v_ashrrev_i32_e32 v13, 31, v12
	s_and_saveexec_b64 s[0:1], vcc
	s_xor_b64 s[0:1], exec, s[0:1]
	v_lshlrev_b64 v[4:5], 7, v[12:13]
	v_lshl_add_u32 v164, v3, 3, v212
	v_lshl_add_u64 v[4:5], s[34:35], 0, v[4:5]
	v_lshl_add_u64 v[4:5], v[164:165], 1, v[4:5]
	s_or_saveexec_b64 s[0:1], s[0:1]
	v_mov_b64_e32 v[8:9], 0x80
	s_xor_b64 exec, exec, s[0:1]
	v_lshlrev_b64 v[4:5], 10, v[12:13]
	v_lshlrev_b32_e32 v8, 3, v3
	v_or_b32_e32 v4, s2, v4
	v_ashrrev_i32_e32 v9, 31, v8
	v_lshl_add_u64 v[4:5], v[4:5], 0, v[8:9]
	v_lshl_add_u64 v[4:5], v[4:5], 1, s[64:65]
	v_mov_b64_e32 v[8:9], 0x800
	s_or_b64 exec, exec, s[0:1]
	v_add_u32_e32 v9, 0x400, v214
	s_mov_b32 s0, 0x2aaaaaab
	v_mul_hi_i32 v10, v9, s0
	v_lshrrev_b32_e32 v11, 31, v10
	v_ashrrev_i32_e32 v10, 2, v10
	v_add_u32_e32 v16, v10, v11
	v_mul_lo_u32 v10, v16, 24
	v_sub_u32_e32 v9, v9, v10
	v_cmp_lt_i32_e32 vcc, 15, v9
	v_ashrrev_i32_e32 v17, 31, v16
	s_and_saveexec_b64 s[0:1], vcc
	s_xor_b64 s[0:1], exec, s[0:1]
	v_lshlrev_b64 v[10:11], 7, v[16:17]
	v_lshl_add_u32 v164, v9, 3, v212
	v_lshl_add_u64 v[10:11], s[34:35], 0, v[10:11]
	v_lshl_add_u64 v[10:11], v[164:165], 1, v[10:11]
	s_or_saveexec_b64 s[0:1], s[0:1]
	v_mov_b64_e32 v[14:15], 0x80
	s_xor_b64 exec, exec, s[0:1]
	v_lshlrev_b64 v[10:11], 10, v[16:17]
	v_lshlrev_b32_e32 v14, 3, v9
	v_or_b32_e32 v10, s2, v10
	v_ashrrev_i32_e32 v15, 31, v14
	v_lshl_add_u64 v[10:11], v[10:11], 0, v[14:15]
	v_lshl_add_u64 v[10:11], v[10:11], 1, s[64:65]
	v_mov_b64_e32 v[14:15], 0x800
	s_or_b64 exec, exec, s[0:1]
	s_lshr_b32 s0, s47, 4
	s_and_b32 s0, s0, 15
	s_lshl_b32 s29, s27, 8
	s_lshl_b32 s1, s0, 11
	s_add_i32 s4, s29, s3
	s_lshl_b32 s5, s27, 2
	s_ashr_i32 s48, s8, 6
	s_ashr_i32 s8, s8, 7
	s_or_b32 s16, s1, 64
	s_lshl_b32 s94, s0, 12
	v_ashrrev_i32_e32 v17, 3, v214
	v_ashrrev_i32_e32 v40, 3, v7
	s_cmp_lt_i32 s48, 8
	v_and_b32_e32 v13, 7, v214
	v_add_u32_e32 v19, s2, v17
	s_mov_b32 s1, 0x10400
	v_add_u32_e32 v41, s2, v40
	s_cselect_b64 s[40:41], -1, 0
	s_lshl_b32 s0, s28, 12
	v_lshlrev_b32_e32 v15, 3, v13
	v_mad_i64_i32 v[20:21], s[12:13], v19, s1, 0
	v_mad_i64_i32 v[36:37], s[12:13], v41, s1, 0
	s_lshl_b32 s27, s48, 5
	v_or_b32_e32 v20, v20, v15
	v_or_b32_e32 v36, v36, v15
	s_movk_i32 s9, 0x190
	s_cmp_gt_i32 s48, 7
	v_lshl_add_u64 v[32:33], v[20:21], 1, s[66:67]
	s_mov_b32 s1, s95
	v_lshl_add_u64 v[36:37], v[36:37], 1, s[66:67]
	v_mul_lo_u32 v7, v12, s9
	s_cselect_b64 s[22:23], -1, 0
	v_lshl_add_u64 v[32:33], v[32:33], 0, s[0:1]
	v_lshl_add_u64 v[36:37], v[36:37], 0, s[0:1]
	v_lshl_add_u32 v218, v3, 4, v7
	v_mul_lo_u32 v3, v6, s9
	v_and_b32_e32 v216, 31, v214
	s_and_b64 s[0:1], s[22:23], exec
	v_lshl_add_u32 v219, v18, 4, v3
	s_cselect_b32 s0, 0, s27
	v_or_b32_e32 v3, s4, v216
	v_add_u32_e32 v3, s0, v3
	v_mov_b64_e32 v[6:7], s[6:7]
	s_movk_i32 s0, 0xc00
	v_mad_i64_i32 v[6:7], s[0:1], v3, s0, v[6:7]
	v_mad_u64_u32 v[20:21], s[12:13], v2, s3, v[0:1]
	v_bfe_u32 v215, v214, 5, 1
	s_mul_i32 s0, s26, 0x180
	s_mov_b32 s1, s95
	global_load_dwordx4 v[20:23], v[20:21], off
	v_mad_u64_u32 v[24:25], s[12:13], v8, s3, v[4:5]
	v_lshl_add_u64 v[6:7], v[6:7], 0, s[0:1]
	v_lshlrev_b32_e32 v186, 4, v215
	v_mov_b32_e32 v187, v165
	global_load_dwordx4 v[24:27], v[24:25], off
	v_mad_u64_u32 v[28:29], s[12:13], v14, s3, v[10:11]
	v_lshl_add_u64 v[6:7], v[6:7], 0, v[186:187]
	global_load_dwordx4 v[28:31], v[28:29], off
	v_mul_lo_u32 v3, v16, s9
	global_load_dwordx4 v[32:35], v[32:33], off
	v_lshl_add_u32 v220, v9, 4, v3
	global_load_dwordx4 v[36:39], v[36:37], off
	s_nop 0
	global_load_dwordx4 v[140:143], v[6:7], off
	global_load_dwordx4 v[136:139], v[6:7], off offset:32
	global_load_dwordx4 v[132:135], v[6:7], off offset:64
	global_load_dwordx4 v[128:131], v[6:7], off offset:96
	global_load_dwordx4 v[124:127], v[6:7], off offset:128
	global_load_dwordx4 v[120:123], v[6:7], off offset:160
	global_load_dwordx4 v[116:119], v[6:7], off offset:192
	global_load_dwordx4 v[112:115], v[6:7], off offset:224
	global_load_dwordx4 v[108:111], v[6:7], off offset:256
	global_load_dwordx4 v[104:107], v[6:7], off offset:288
	global_load_dwordx4 v[100:103], v[6:7], off offset:320
	global_load_dwordx4 v[96:99], v[6:7], off offset:352
	v_lshlrev_b32_e32 v3, 3, v214
	v_lshlrev_b32_e32 v7, 4, v13
	v_and_b32_e32 v3, 8, v3
	s_movk_i32 s0, 0x60
	v_and_or_b32 v6, v7, s0, v3
	v_add_u32_e32 v3, 0, v219
	s_movk_i32 s4, 0x90
	v_mad_u64_u32 v[188:189], s[0:1], v17, s4, v[6:7]
	v_mad_u64_u32 v[190:191], s[0:1], v40, s4, v[6:7]
	s_lshl_b32 s0, s48, 8
	s_add_i32 s12, s0, 0
	v_mad_u64_u32 v[198:199], s[0:1], v2, s16, v[0:1]
	v_mov_b64_e32 v[0:1], s[94:95]
	s_mov_b32 s4, 0x20800
	v_lshlrev_b32_e32 v200, 6, v2
	v_mad_u64_u32 v[192:193], s[0:1], v14, s16, v[10:11]
	v_lshlrev_b32_e32 v164, 6, v14
	v_mov_b32_e32 v14, v165
	v_mov_b32_e32 v15, v165
	v_and_b32_e32 v187, 63, v214
	s_add_i32 s12, s12, 0x15800
	v_mad_u64_u32 v[194:195], s[0:1], v8, s16, v[4:5]
	v_lshlrev_b32_e32 v196, 6, v8
	v_mov_b32_e32 v4, v165
	v_mov_b32_e32 v5, v165
	v_mov_b32_e32 v6, v165
	v_mov_b32_e32 v8, v165
	v_mov_b32_e32 v9, v165
	v_mov_b32_e32 v10, v165
	v_mov_b32_e32 v11, v165
	v_mov_b32_e32 v12, v165
	v_mov_b32_e32 v13, v165
	s_mov_b32 s9, 0
	s_add_i32 s10, s8, s5
	v_cmp_gt_u32_e64 s[38:39], 32, v187
	v_lshl_add_u32 v189, v216, 2, s12
	s_or_b32 s13, s5, 3
	v_mov_b32_e32 v197, v165
	v_mov_b32_e32 v201, v165
	v_mov_b32_e32 v223, 0xf149f2ca
	v_mov_b32_e32 v191, 0
	s_waitcnt vmcnt(0)
; #define ATT_ISSUE(t) do { const int trow_ = (sample && (t) == 32) ? kvnew : kv0 + 64 * (t); \
;         _Pragma("unroll") for (int i_ = 0; i_ < 3; ++i_) kreg[i_] = *(const GAS u32x4*)(kb[i_] + (size_t)trow_ * ks[i_]); \
;         _Pragma("unroll") for (int i_ = 0; i_ < 2; ++i_) vreg[i_] = *(const GAS u32x4*)(vb[i_] + (size_t)trow_ * 2); } while (0)
; #define ATT_WRITE(buf) do { _Pragma("unroll") for (int i_ = 0; i_ < 3; ++i_) *(LAS u32x4*)(lds + OFF_K + (buf) * KBUF + kd[i_]) = kreg[i_]; \
;         _Pragma("unroll") for (int i_ = 0; i_ < 2; ++i_) { LAS u32x2* d_ = (LAS u32x2*)(lds + OFF_V + (buf) * VBUF + vd[i_]); d_[0] = (u32x2){vreg[i_].x, vreg[i_].y}; d_[2] = (u32x2){vreg[i_].z, vreg[i_].w}; } } while (0)
; __device__ __forceinline__ void unit(LAS unsigned char* lds, const Tensors& T, int h, int qrow0, int nact, bool sample, int limbase, int kv0, int kvnew, int nt) {
;     ...
;     ATT_WRITE(0);
;     __syncthreads();
;     for (int t = 0; t < nt; ++t) {
;         const int buf = t & 1;
;         if (t + 1 < nt) ATT_ISSUE(t + 1);
	ds_write_b128 v3, v[20:23]
	v_add_u32_e32 v3, 0, v218
	ds_write_b128 v3, v[24:27]
	v_add_u32_e32 v3, 0, v220
	ds_write_b128 v3, v[28:31]
	v_add_u32_e32 v3, 0, v188
	v_add_u32_e32 v3, 0xc800, v3
	ds_write2_b64 v3, v[32:33], v[34:35] offset1:2
	v_add_u32_e32 v3, 0, v190
	v_add_u32_e32 v3, 0xc800, v3
	ds_write2_b64 v3, v[36:37], v[38:39] offset1:2
	v_mul_u32_u24_e32 v3, 0x190, v216
	v_add3_u32 v221, 0, v3, v186
	v_lshlrev_b32_e32 v3, 8, v216
	v_sub_u32_e32 v217, v221, v3
	v_mad_i64_i32 v[2:3], s[0:1], v41, s4, v[0:1]
	v_mad_i64_i32 v[0:1], s[0:1], v19, s4, v[0:1]
	v_or_b32_e32 v2, v2, v7
	v_or_b32_e32 v0, v0, v7
	v_lshl_add_u64 v[202:203], s[74:75], 0, v[2:3]
	v_lshl_add_u64 v[204:205], s[74:75], 0, v[0:1]
	v_mov_b32_e32 v0, v165
	v_mov_b32_e32 v1, v165
	v_mov_b32_e32 v2, v165
	v_mov_b32_e32 v3, v165
	v_mov_b32_e32 v7, v165
	v_mov_b64_e32 v[62:63], v[14:15]
	v_mov_b64_e32 v[46:47], v[14:15]
	v_mov_b64_e32 v[30:31], v[14:15]
	v_mov_b64_e32 v[60:61], v[12:13]
	v_mov_b64_e32 v[58:59], v[10:11]
	v_mov_b64_e32 v[56:57], v[8:9]
	v_mov_b64_e32 v[54:55], v[6:7]
	v_mov_b64_e32 v[52:53], v[4:5]
	v_mov_b64_e32 v[50:51], v[2:3]
	v_mov_b64_e32 v[48:49], v[0:1]
	v_mov_b64_e32 v[44:45], v[12:13]
	v_mov_b64_e32 v[42:43], v[10:11]
	v_mov_b64_e32 v[40:41], v[8:9]
	v_mov_b64_e32 v[38:39], v[6:7]
	v_mov_b64_e32 v[36:37], v[4:5]
	v_mov_b64_e32 v[34:35], v[2:3]
	v_mov_b64_e32 v[32:33], v[0:1]
	v_mov_b64_e32 v[28:29], v[12:13]
	v_mov_b64_e32 v[26:27], v[10:11]
	v_mov_b64_e32 v[24:25], v[8:9]
	v_mov_b64_e32 v[22:23], v[6:7]
	v_mov_b64_e32 v[20:21], v[4:5]
	v_mov_b64_e32 v[18:19], v[2:3]
	v_mov_b64_e32 v[16:17], v[0:1]
	s_waitcnt lgkmcnt(0)
	s_barrier
	v_readfirstlane_b32 s0, v206
	s_nop 3
	s_cmp_ge_u32 s0, 0x100
	s_cbranch_scc1 .Lat_prio
	s_setprio 1
.Lat_prio:
	v_readfirstlane_b32 s100, v206
	s_nop 0
	s_lshr_b32 s100, s100, 8
	s_cmp_eq_u32 s100, 0
	s_cbranch_scc1 .Lat_p0
	global_load_dwordx4 v[160:163], v[198:199], off
	global_load_dwordx4 v[156:159], v[194:195], off
	global_load_dwordx4 v[152:155], v[192:193], off
	global_load_dwordx4 v[148:151], v[204:205], off
	global_load_dwordx4 v[144:147], v[202:203], off
	v_lshl_add_u64 v[192:193], v[192:193], 0, v[164:165]
	v_lshl_add_u64 v[194:195], v[194:195], 0, v[196:197]
	v_lshl_add_u64 v[198:199], v[198:199], 0, v[200:201]
	v_lshl_add_u64 v[202:203], v[202:203], 0, s[14:15]
	v_lshl_add_u64 v[204:205], v[204:205], 0, s[14:15]
.Lat_p0:
.LBB0_904:
	s_and_b32 s16, s9, 1
	s_cmp_lg_u32 s100, 0
	s_cbranch_scc1 .Lat_topB
	global_load_dwordx4 v[160:163], v[198:199], off
	global_load_dwordx4 v[156:159], v[194:195], off
	global_load_dwordx4 v[152:155], v[192:193], off
	global_load_dwordx4 v[148:151], v[204:205], off
	global_load_dwordx4 v[144:147], v[202:203], off
	s_branch .Lat_topE
.Lat_topB:
	s_xor_b32 s0, s16, 1
	s_mul_i32 s1, s0, 0x6400
	s_add_i32 s1, s1, 0
	v_add_u32_e32 v64, s1, v219
	s_waitcnt vmcnt(4)
	ds_write_b128 v64, v[160:163]
	v_add_u32_e32 v64, s1, v218
	s_mulk_i32 s0, 0xe400
	s_waitcnt vmcnt(3)
	ds_write_b128 v64, v[156:159]
	v_add_u32_e32 v64, s1, v220
	s_add_i32 s1, s1, s0
	s_waitcnt vmcnt(2)
	ds_write_b128 v64, v[152:155]
	v_add_u32_e32 v64, s1, v188
	v_add_u32_e32 v64, 0xc800, v64
	s_waitcnt vmcnt(1)
	ds_write2_b64 v64, v[148:149], v[150:151] offset1:2
	v_add_u32_e32 v64, s1, v190
	v_add_u32_e32 v64, 0xc800, v64
	s_waitcnt vmcnt(0)
	ds_write2_b64 v64, v[144:145], v[146:147] offset1:2
	s_waitcnt lgkmcnt(0)
	s_add_i32 s0, s9, 2
	s_cmp_gt_u32 s0, s13
	s_cbranch_scc1 .Lat_topE
	global_load_dwordx4 v[160:163], v[198:199], off
	global_load_dwordx4 v[156:159], v[194:195], off
	global_load_dwordx4 v[152:155], v[192:193], off
	global_load_dwordx4 v[148:151], v[204:205], off
	global_load_dwordx4 v[144:147], v[202:203], off
	v_lshl_add_u64 v[192:193], v[192:193], 0, v[164:165]
	v_lshl_add_u64 v[194:195], v[194:195], 0, v[196:197]
	v_lshl_add_u64 v[198:199], v[198:199], 0, v[200:201]
	v_lshl_add_u64 v[202:203], v[202:203], 0, s[14:15]
	v_lshl_add_u64 v[204:205], v[204:205], 0, s[14:15]
; #define LAS __attribute__((address_space(3)))
; __device__ __forceinline__ int crow(int r, int hi) { return (r & 3) + 8 * (r >> 2) + 4 * hi; }
; #define MFMA32(a, b, c) __builtin_amdgcn_mfma_f32_32x32x16_bf16((a), (b), (c), 0, 0, 0)
; __device__ __forceinline__ void unit(LAS unsigned char* lds, const Tensors& T, int h, int qrow0, int nact, bool sample, int limbase, int kv0, int kvnew, int nt) {
;     ...
;         if (active && t <= lim) {
;             const LAS unsigned char* kp = lds + OFF_K + buf * KBUF + r32 * KP + hi * 16;
;             f32x16 p0, p1;
; #pragma unroll
;             for (int r = 0; r < 16; ++r) { p0[r] = 0.f; p1[r] = 0.f; }
;             { bf16x8 kf[4][2];
; #pragma unroll
;               for (int i = 0; i < 4; ++i) { kf[i][0] = *(const LAS bf16x8*)(kp + i * 32); kf[i][1] = *(const LAS bf16x8*)(kp + 32 * KP + i * 32); }
;               __builtin_amdgcn_sched_barrier(0);
; #pragma unroll
;               for (int i = 0; i < 12; ++i) {
;                   p0 = MFMA32(kf[i & 3][0], qf[i], p0); p1 = MFMA32(kf[i & 3][1], qf[i], p1);
;                   if (i + 4 < 12) { kf[i & 3][0] = *(const LAS bf16x8*)(kp + (i + 4) * 32); kf[i & 3][1] = *(const LAS bf16x8*)(kp + 32 * KP + (i + 4) * 32); }
;                   __builtin_amdgcn_sched_barrier(0);
;               } }
;             float rm = fmaxf(p0[0], p1[0]);
; #pragma unroll
;             for (int r = 1; r < 16; ++r) rm = fmaxf(rm, fmaxf(p0[r], p1[r]));
;             { const auto rr = __builtin_amdgcn_permlane32_swap(__float_as_uint(rm), __float_as_uint(rm), false, false);
;               rm = fmaxf(__uint_as_float(rr[0]), __uint_as_float(rr[1])); }
;             const bool need = rm > mrun + 8.0f;
;             if (__builtin_amdgcn_ballot_w64(need) != 0ull) {
;                 const float mn = need ? rm : mrun; const float alpha = __builtin_amdgcn_exp2f(mrun - mn); mrun = mn; lrun *= alpha;
;                 if (hi == 0) scr[r32] = alpha;
;                 asm volatile("s_waitcnt lgkmcnt(0)" ::: "memory");
; #pragma unroll
;                 for (int r = 0; r < 16; ++r) { const float f = scr[crow(r, hi)];
; #pragma unroll
;                     for (int d = 0; d < 4; ++d) o[d][r] *= f; }
;                 asm volatile("s_waitcnt lgkmcnt(0)" ::: "memory");
;             }
.Lat_topE:
	s_cmp_gt_i32 s9, s10
	s_cselect_b64 s[0:1], -1, 0
	s_or_b64 s[0:1], s[22:23], s[0:1]
	s_and_b64 vcc, exec, s[0:1]
	s_cbranch_vccnz .LBB0_909
	s_mul_i32 s0, s16, 0x6400
	v_add_u32_e32 v222, s0, v221
	ds_read_b128 v[64:67], v222
	ds_read_b128 v[224:227], v222 offset:32
	ds_read_b128 v[68:71], v222 offset:12800
	ds_read_b128 v[228:231], v222 offset:12832
	ds_read_b128 v[232:235], v222 offset:64
	ds_read_b128 v[236:239], v222 offset:96
	ds_read_b128 v[240:243], v222 offset:12864
	ds_read_b128 v[244:247], v222 offset:12896
	s_waitcnt lgkmcnt(7)
	v_mfma_f32_32x32x16_bf16 v[80:95], v[64:67], v[140:143], 0
	ds_read_b128 v[248:251], v222 offset:128
	ds_read_b128 v[166:169], v222 offset:12928
	s_waitcnt lgkmcnt(7)
	v_mfma_f32_32x32x16_bf16 v[64:79], v[68:71], v[140:143], 0
	v_mfma_f32_32x32x16_bf16 v[80:95], v[224:227], v[136:139], v[80:95]
	s_waitcnt lgkmcnt(6)
	v_mfma_f32_32x32x16_bf16 v[64:79], v[228:231], v[136:139], v[64:79]
	ds_read_b128 v[224:227], v222 offset:160
	ds_read_b128 v[228:231], v222 offset:12960
	s_waitcnt lgkmcnt(7)
	v_mfma_f32_32x32x16_bf16 v[80:95], v[232:235], v[132:135], v[80:95]
	s_waitcnt lgkmcnt(5)
	v_mfma_f32_32x32x16_bf16 v[64:79], v[240:243], v[132:135], v[64:79]
	ds_read_b128 v[232:235], v222 offset:192
	ds_read_b128 v[240:243], v222 offset:12992
	v_mfma_f32_32x32x16_bf16 v[80:95], v[236:239], v[128:131], v[80:95]
	s_waitcnt lgkmcnt(6)
	v_mfma_f32_32x32x16_bf16 v[64:79], v[244:247], v[128:131], v[64:79]
	ds_read_b128 v[236:239], v222 offset:224
	ds_read_b128 v[244:247], v222 offset:13024
	s_waitcnt lgkmcnt(7)
	v_mfma_f32_32x32x16_bf16 v[80:95], v[248:251], v[124:127], v[80:95]
	s_waitcnt lgkmcnt(6)
	v_mfma_f32_32x32x16_bf16 v[64:79], v[166:169], v[124:127], v[64:79]
	ds_read_b128 v[166:169], v222 offset:256
	ds_read_b128 v[248:251], v222 offset:13056
	s_waitcnt lgkmcnt(7)
	v_mfma_f32_32x32x16_bf16 v[80:95], v[224:227], v[120:123], v[80:95]
	s_waitcnt lgkmcnt(6)
	v_mfma_f32_32x32x16_bf16 v[64:79], v[228:231], v[120:123], v[64:79]
	ds_read_b128 v[224:227], v222 offset:288
	ds_read_b128 v[228:231], v222 offset:13088
	s_waitcnt lgkmcnt(7)
	v_mfma_f32_32x32x16_bf16 v[80:95], v[232:235], v[116:119], v[80:95]
	s_waitcnt lgkmcnt(6)
	v_mfma_f32_32x32x16_bf16 v[64:79], v[240:243], v[116:119], v[64:79]
	ds_read_b128 v[232:235], v222 offset:320
	ds_read_b128 v[240:243], v222 offset:13120
	s_waitcnt lgkmcnt(7)
	v_mfma_f32_32x32x16_bf16 v[80:95], v[236:239], v[112:115], v[80:95]
	s_waitcnt lgkmcnt(6)
	v_mfma_f32_32x32x16_bf16 v[64:79], v[244:247], v[112:115], v[64:79]
	ds_read_b128 v[236:239], v222 offset:352
	ds_read_b128 v[244:247], v222 offset:13152
	s_waitcnt lgkmcnt(7)
	v_mfma_f32_32x32x16_bf16 v[80:95], v[166:169], v[108:111], v[80:95]
	s_waitcnt lgkmcnt(6)
	v_mfma_f32_32x32x16_bf16 v[64:79], v[248:251], v[108:111], v[64:79]
	s_waitcnt lgkmcnt(5)
	v_mfma_f32_32x32x16_bf16 v[80:95], v[224:227], v[104:107], v[80:95]
	s_waitcnt lgkmcnt(4)
	v_mfma_f32_32x32x16_bf16 v[64:79], v[228:231], v[104:107], v[64:79]
	s_waitcnt lgkmcnt(3)
	v_mfma_f32_32x32x16_bf16 v[80:95], v[232:235], v[100:103], v[80:95]
	s_waitcnt lgkmcnt(2)
	v_mfma_f32_32x32x16_bf16 v[64:79], v[240:243], v[100:103], v[64:79]
	s_waitcnt lgkmcnt(1)
	v_mfma_f32_32x32x16_bf16 v[80:95], v[236:239], v[96:99], v[80:95]
	s_waitcnt lgkmcnt(0)
	v_mfma_f32_32x32x16_bf16 v[64:79], v[244:247], v[96:99], v[64:79]
	s_nop 11
	v_max_f32_e32 v166, v81, v65
	v_max_f32_e32 v167, v82, v66
	v_max3_f32 v166, v80, v64, v166
	v_max_f32_e32 v168, v83, v67
	v_max3_f32 v166, v166, v167, v168
	v_max_f32_e32 v167, v84, v68
	v_max_f32_e32 v168, v85, v69
	v_max3_f32 v166, v166, v167, v168
	v_max_f32_e32 v167, v86, v70
	v_max_f32_e32 v168, v87, v71
	v_max3_f32 v166, v166, v167, v168
	v_max_f32_e32 v167, v88, v72
	v_max_f32_e32 v168, v89, v73
	v_max3_f32 v166, v166, v167, v168
	v_max_f32_e32 v167, v90, v74
	v_max_f32_e32 v168, v91, v75
	v_max3_f32 v166, v166, v167, v168
	v_max_f32_e32 v167, v92, v76
	v_max_f32_e32 v168, v93, v77
	v_max3_f32 v166, v166, v167, v168
	v_max_f32_e32 v167, v94, v78
	v_max_f32_e32 v168, v95, v79
	v_max3_f32 v166, v166, v167, v168
	v_mov_b32_e32 v167, v166
	s_nop 1
	v_permlane32_swap_b32_e32 v166, v167
	v_max_f32_e32 v222, v166, v167
	v_add_f32_e32 v166, 0x41000000, v223
	v_cmp_gt_f32_e32 vcc, v222, v166
	s_cbranch_vccz .LBB0_910
	s_nop 0
	v_cndmask_b32_e32 v222, v223, v222, vcc
	v_sub_f32_e32 v166, v223, v222
	v_exp_f32_e32 v223, v166
	s_and_saveexec_b64 s[0:1], s[38:39]
	ds_write_b32 v189, v223
	s_or_b64 exec, exec, s[0:1]
	v_mul_f32_e32 v191, v191, v223
	s_waitcnt lgkmcnt(0)
	v_add_u32_e32 v223, s12, v186
	ds_read_b128 v[166:169], v223
	ds_read_b128 v[224:227], v223 offset:32
	ds_read_b128 v[228:231], v223 offset:64
	ds_read_b128 v[232:235], v223 offset:96
	s_waitcnt lgkmcnt(0)
	s_waitcnt lgkmcnt(3)
	v_pk_mul_f32 v[2:3], v[2:3], v[168:169]
	s_waitcnt lgkmcnt(2)
	v_pk_mul_f32 v[4:5], v[4:5], v[224:225]
	s_waitcnt lgkmcnt(1)
	v_pk_mul_f32 v[8:9], v[8:9], v[228:229]
	s_waitcnt lgkmcnt(0)
	v_pk_mul_f32 v[12:13], v[12:13], v[232:233]
	v_pk_mul_f32 v[14:15], v[14:15], v[234:235]
	v_pk_mul_f32 v[10:11], v[10:11], v[230:231]
	v_pk_mul_f32 v[6:7], v[6:7], v[226:227]
	v_pk_mul_f32 v[0:1], v[0:1], v[166:167]
	v_pk_mul_f32 v[60:61], v[60:61], v[232:233]
	v_pk_mul_f32 v[56:57], v[56:57], v[228:229]
	v_pk_mul_f32 v[52:53], v[52:53], v[224:225]
	v_pk_mul_f32 v[62:63], v[62:63], v[234:235]
	v_pk_mul_f32 v[58:59], v[58:59], v[230:231]
	v_pk_mul_f32 v[54:55], v[54:55], v[226:227]
	v_pk_mul_f32 v[50:51], v[50:51], v[168:169]
	v_pk_mul_f32 v[48:49], v[48:49], v[166:167]
	v_pk_mul_f32 v[44:45], v[44:45], v[232:233]
	v_pk_mul_f32 v[40:41], v[40:41], v[228:229]
	v_pk_mul_f32 v[36:37], v[36:37], v[224:225]
	v_pk_mul_f32 v[46:47], v[46:47], v[234:235]
	v_pk_mul_f32 v[42:43], v[42:43], v[230:231]
	v_pk_mul_f32 v[38:39], v[38:39], v[226:227]
	v_pk_mul_f32 v[34:35], v[34:35], v[168:169]
	v_pk_mul_f32 v[32:33], v[32:33], v[166:167]
	v_pk_mul_f32 v[28:29], v[28:29], v[232:233]
	v_pk_mul_f32 v[24:25], v[24:25], v[228:229]
	v_pk_mul_f32 v[20:21], v[20:21], v[224:225]
	v_pk_mul_f32 v[30:31], v[30:31], v[234:235]
	v_pk_mul_f32 v[26:27], v[26:27], v[230:231]
	v_pk_mul_f32 v[22:23], v[22:23], v[226:227]
	v_pk_mul_f32 v[18:19], v[18:19], v[168:169]
	v_pk_mul_f32 v[16:17], v[16:17], v[166:167]
	s_branch .LBB0_911

; #define ATT_WRITE(buf) do { _Pragma("unroll") for (int i_ = 0; i_ < 3; ++i_) *(LAS u32x4*)(lds + OFF_K + (buf) * KBUF + kd[i_]) = kreg[i_]; \
;         _Pragma("unroll") for (int i_ = 0; i_ < 2; ++i_) { LAS u32x2* d_ = (LAS u32x2*)(lds + OFF_V + (buf) * VBUF + vd[i_]); d_[0] = (u32x2){vreg[i_].x, vreg[i_].y}; d_[2] = (u32x2){vreg[i_].z, vreg[i_].w}; } } while (0)
; __device__ __forceinline__ void unit(LAS unsigned char* lds, const Tensors& T, int h, int qrow0, int nact, bool sample, int limbase, int kv0, int kvnew, int nt) {
;     ...
;     for (int t = 0; t < nt; ++t) {
;     ...
;         if (t + 1 < nt) ATT_WRITE(buf ^ 1);
;         __syncthreads();
.LBB0_912:
	s_cmp_lg_u32 s100, 0
	s_cbranch_scc1 .Lat_endw
	s_xor_b32 s0, s16, 1
	s_mul_i32 s1, s0, 0x6400
	s_add_i32 s1, s1, 0
	v_add_u32_e32 v64, s1, v219
	s_waitcnt vmcnt(4)
	ds_write_b128 v64, v[160:163]
	v_add_u32_e32 v64, s1, v218
	s_mulk_i32 s0, 0xe400
	s_waitcnt vmcnt(3)
	ds_write_b128 v64, v[156:159]
	v_add_u32_e32 v64, s1, v220
	s_add_i32 s1, s1, s0
	s_waitcnt vmcnt(2)
	ds_write_b128 v64, v[152:155]
	v_add_u32_e32 v64, s1, v188
	v_add_u32_e32 v64, 0xc800, v64
	s_waitcnt vmcnt(1)
	ds_write2_b64 v64, v[148:149], v[150:151] offset1:2
	v_add_u32_e32 v64, s1, v190
	v_add_u32_e32 v64, 0xc800, v64
	s_waitcnt vmcnt(0)
	ds_write2_b64 v64, v[144:145], v[146:147] offset1:2
	v_lshl_add_u64 v[192:193], v[192:193], 0, v[164:165]
	v_lshl_add_u64 v[194:195], v[194:195], 0, v[196:197]
	v_lshl_add_u64 v[198:199], v[198:199], 0, v[200:201]
	v_lshl_add_u64 v[202:203], v[202:203], 0, s[14:15]
	v_lshl_add_u64 v[204:205], v[204:205], 0, s[14:15]
.Lat_endw:
	s_add_i32 s9, s9, 1
	s_waitcnt lgkmcnt(0)
	s_barrier
	s_cmp_eq_u32 s13, s9
	s_cbranch_scc1 .LBB0_914
	v_mov_b32_e32 v223, v222
	s_branch .LBB0_904

; __global__ void __launch_bounds__(NWAVES * 64, 2) mega_fwd(Args a) {
	.amdhsa_kernel _Z8mega_fwd4Args
		.amdhsa_group_segment_fixed_size 0
		.amdhsa_private_segment_fixed_size 0
		.amdhsa_kernarg_size 432
		.amdhsa_user_sgpr_count 2
		.amdhsa_user_sgpr_dispatch_ptr 0
		.amdhsa_user_sgpr_queue_ptr 0
		.amdhsa_user_sgpr_kernarg_segment_ptr 1
		.amdhsa_user_sgpr_dispatch_id 0
		.amdhsa_user_sgpr_kernarg_preload_length 0
		.amdhsa_user_sgpr_kernarg_preload_offset 0
		.amdhsa_user_sgpr_private_segment_size 0
		.amdhsa_uses_dynamic_stack 0
		.amdhsa_enable_private_segment 0
		.amdhsa_system_sgpr_workgroup_id_x 1
		.amdhsa_system_sgpr_workgroup_id_y 0
		.amdhsa_system_sgpr_workgroup_id_z 0
		.amdhsa_system_sgpr_workgroup_info 0
		.amdhsa_system_vgpr_workitem_id 2
		.amdhsa_next_free_vgpr 256
		.amdhsa_next_free_sgpr 102
		.amdhsa_accum_offset 256
		.amdhsa_reserve_vcc 1
		.amdhsa_float_round_mode_32 0
		.amdhsa_float_round_mode_16_64 0
		.amdhsa_float_denorm_mode_32 3
		.amdhsa_float_denorm_mode_16_64 3
		.amdhsa_dx10_clamp 1
		.amdhsa_ieee_mode 1
		.amdhsa_fp16_overflow 0
		.amdhsa_tg_split 0
		.amdhsa_exception_fp_ieee_invalid_op 0
		.amdhsa_exception_fp_denorm_src 0
		.amdhsa_exception_fp_ieee_div_zero 0
		.amdhsa_exception_fp_ieee_overflow 0
		.amdhsa_exception_fp_ieee_underflow 0
		.amdhsa_exception_fp_ieee_inexact 0
		.amdhsa_exception_int_div_zero 0
	.end_amdhsa_kernel

; __global__ void __launch_bounds__(NWAVES * 64, 2) mega_fwd(Args a) {
amdhsa.kernels:
  - .agpr_count:     0
    .args:
      - .offset:         0
        .size:           176
        .value_kind:     by_value
      - .offset:         176
        .size:           4
        .value_kind:     hidden_block_count_x
      - .offset:         180
        .size:           4
        .value_kind:     hidden_block_count_y
      - .offset:         184
        .size:           4
        .value_kind:     hidden_block_count_z
      - .offset:         188
        .size:           2
        .value_kind:     hidden_group_size_x
      - .offset:         190
        .size:           2
        .value_kind:     hidden_group_size_y
      - .offset:         192
        .size:           2
        .value_kind:     hidden_group_size_z
      - .offset:         194
        .size:           2
        .value_kind:     hidden_remainder_x
      - .offset:         196
        .size:           2
        .value_kind:     hidden_remainder_y
      - .offset:         198
        .size:           2
        .value_kind:     hidden_remainder_z
      - .offset:         216
        .size:           8
        .value_kind:     hidden_global_offset_x
      - .offset:         224
        .size:           8
        .value_kind:     hidden_global_offset_y
      - .offset:         232
        .size:           8
        .value_kind:     hidden_global_offset_z
      - .offset:         240
        .size:           2
        .value_kind:     hidden_grid_dims
      - .offset:         264
        .size:           8
        .value_kind:     hidden_multigrid_sync_arg
      - .offset:         296
        .size:           4
        .value_kind:     hidden_dynamic_lds_size
    .group_segment_fixed_size: 0
    .kernarg_segment_align: 8
    .kernarg_segment_size: 432
    .language:       OpenCL C
    .language_version:
      - 2
      - 0
    .max_flat_workgroup_size: 512
    .name:           _Z8mega_fwd4Args
    .private_segment_fixed_size: 0
    .sgpr_count:     108
    .sgpr_spill_count: 121
    .symbol:         _Z8mega_fwd4Args.kd
    .uniform_work_group_size: 1
    .uses_dynamic_stack: false
    .vgpr_count:     256
    .vgpr_spill_count: 0
    .wavefront_size: 64
